# layer-1 cooperative-groups grid.sync replaced by the sharded counter barrier
# baseline (speedup 1.0000x reference)
; #define LAS __attribute__((address_space(3)))
; DI int opq0() { int z = 0; asm volatile("" : "+s"(z)); return z; }
; DI void phase_norm_x(const float* src_lo, const float* src_hi, int split_row, int row0, bf16_t* xb, int gw, int ngw, int lane) {
;     for (int r = gw; r < MC; r += ngw) {
;         const int R = row0 + r; const float* src = (R < split_row ? src_lo + (size_t)R * 1024 : src_hi + (size_t)(R - split_row) * 1024);
;         f32x4 v[4]; float ss = 0.f;
; #pragma unroll
;         for (int j = 0; j < 4; ++j) { v[j] = *(const f32x4*)(src + j * 256 + lane * 4); ss += v[j][0] * v[j][0] + v[j][1] * v[j][1] + v[j][2] * v[j][2] + v[j][3] * v[j][3]; }
;         ss = wave_sum(ss); const float rs = rsqrtf(ldexpf(ss + 1024.0f * EPS, -10));
; __global__ void __launch_bounds__(512, 2) mega(Params P) {
;     ...
;         { TID_VARS; if (layer == 0 && tid == 0) *(volatile LAS unsigned*)(lds + 131072) = 0u; if (layer == 0 && blk == 0) { unsigned* bw = (unsigned*)(P.ws + opq0() + WS_BAR); for (int i = tid; i < 4096; i += 512) bw[i] = 0u; } phase_prep(P, layer, blk * 512 + tid, G * 512); }
;         if (layer == 0) { const int z = opq0(); TID_VARS; phase_norm_x(P.in[I_XP + z], P.in[I_XS + z], MC, 0, WSP(bf16_t, WS_VT), blk * 8 + wave, G * 8, lane); }
;         grid.sync();
.LBB0_330:
	s_mov_b32 s100, s38
	s_or_b64 exec, exec, s[12:13]
	s_andn2_b64 vcc, exec, s[38:39]
	s_mov_b32 s19, 0x800000
	s_waitcnt lgkmcnt(0)
	v_readlane_b32 s42, v254, 58
	v_readlane_b32 s43, v254, 59
	s_cbranch_vccnz .LBB0_335
	s_mov_b32 s8, s94
	v_mov_b32_e32 v2, v232
	v_readlane_b32 s6, v254, 23
	v_ashrrev_i32_e32 v0, 6, v2
	v_readlane_b32 s7, v254, 24
	v_add_u32_e32 v4, s6, v0
	v_cmp_gt_i32_e32 vcc, s1, v4
	s_and_saveexec_b64 s[6:7], vcc
	v_readlane_b32 s14, v254, 19
	v_readlane_b32 s15, v254, 20
	s_movk_i32 s2, 0x3fff
	s_cbranch_execz .LBB0_334
	v_and_b32_e32 v1, 64, v233
	v_add_u32_e32 v1, 64, v1
	v_xor_b32_e32 v3, 32, v233
	v_cmp_lt_i32_e32 vcc, v3, v1
	s_ashr_i32 s9, s8, 31
	s_lshl_b64 s[10:11], s[8:9], 3
	v_cndmask_b32_e32 v3, v233, v3, vcc
	v_lshlrev_b32_e32 v5, 2, v3
	v_xor_b32_e32 v3, 16, v233
	v_cmp_lt_i32_e32 vcc, v3, v1
	s_add_u32 s10, s66, s10
	s_addc_u32 s11, s67, s11
	v_cndmask_b32_e32 v3, v233, v3, vcc
	v_lshlrev_b32_e32 v6, 2, v3
	v_xor_b32_e32 v3, 8, v233
	v_cmp_lt_i32_e32 vcc, v3, v1
	s_load_dwordx2 s[10:11], s[10:11], 0x0
	v_readlane_b32 s12, v254, 23
	v_cndmask_b32_e32 v3, v233, v3, vcc
	v_lshlrev_b32_e32 v7, 2, v3
	v_xor_b32_e32 v3, 4, v233
	v_cmp_lt_i32_e32 vcc, v3, v1
	v_readlane_b32 s13, v254, 24
	v_and_b32_e32 v11, 63, v2
	v_cndmask_b32_e32 v3, v233, v3, vcc
	v_lshlrev_b32_e32 v8, 2, v3
	v_xor_b32_e32 v3, 2, v233
	v_cmp_lt_i32_e32 vcc, v3, v1
	v_readlane_b32 s0, v254, 21
	s_add_u32 s8, s0, s8
	v_cndmask_b32_e32 v3, v233, v3, vcc
	v_lshlrev_b32_e32 v9, 2, v3
	v_xor_b32_e32 v3, 1, v233
	v_cmp_lt_i32_e32 vcc, v3, v1
	v_readlane_b32 s0, v254, 22
	s_addc_u32 s9, s0, s9
	v_cndmask_b32_e32 v1, v233, v3, vcc
	v_lshlrev_b32_e32 v10, 2, v1
	v_ashrrev_i32_e32 v1, 31, v0
	v_lshl_add_u64 v[12:13], s[12:13], 0, v[0:1]
	v_lshlrev_b64 v[0:1], 12, v[12:13]
	v_lshl_or_b32 v0, v11, 4, v0
	v_lshlrev_b64 v[2:3], 11, v[12:13]
	s_waitcnt lgkmcnt(0)
	v_lshl_add_u64 v[0:1], s[10:11], 0, v[0:1]
	s_mov_b64 s[10:11], 0xc00
	v_lshl_or_b32 v2, v11, 3, v2
	v_lshl_add_u64 v[0:1], v[0:1], 0, s[10:11]
	v_lshl_add_u64 v[2:3], s[8:9], 0, v[2:3]
	s_mov_b64 s[8:9], 0

; #define LAS __attribute__((address_space(3)))
; DI int opq0() { int z = 0; asm volatile("" : "+s"(z)); return z; }
; DI int tid_opq() { int t = threadIdx.x; asm volatile("" : "+v"(t)); return t; }
; DI unsigned xb_ld(unsigned* p)              { return __hip_atomic_load(p, __ATOMIC_RELAXED, __HIP_MEMORY_SCOPE_AGENT); }
; DI unsigned xb_add(unsigned* p, unsigned v) { return __hip_atomic_fetch_add(p, v, __ATOMIC_RELAXED, __HIP_MEMORY_SCOPE_AGENT); }
; DI void flat_barrier(unsigned char* wsb, LAS unsigned char* ldsb) {
;     asm volatile("s_waitcnt vmcnt(0)" ::: "memory");
;     __syncthreads();
;     if (tid_opq() == 0) {
;         unsigned* cnt = (unsigned*)(wsb + opq0() + WS_BAR) + 64;
;         const unsigned G = gridDim.x;
;         __builtin_amdgcn_fence(__ATOMIC_RELEASE, "agent");
;         asm volatile("s_waitcnt vmcnt(0)" ::: "memory");
;         volatile LAS unsigned* st = (volatile LAS unsigned*)(ldsb + 131072);
;         const unsigned k = st[0] + 1u; st[0] = k;
;         (void)xb_add(cnt, 1u);
;         const unsigned target = k * G;
;         unsigned sp = 0u;
;         while (xb_ld(cnt) < target) { __builtin_amdgcn_s_sleep(1); if (++sp > (1u << 24)) break; }
; __global__ void __launch_bounds__(512, 2) mega(Params P) {
;     ...
;         grid.sync();
.LBB0_335:
	s_cmp_lg_u32 s100, 0
	s_cbranch_scc1 .Lcg_orig
	s_waitcnt vmcnt(0)
	s_barrier
	v_mov_b32_e32 v0, v232
	s_nop 0
	v_cmp_gt_u32_e32 vcc, 16, v0
	s_and_saveexec_b64 s[6:7], vcc
	s_cbranch_execz .LBB0_345
	buffer_wbl2 sc1
	s_waitcnt vmcnt(0)
	v_readlane_b32 s0, v254, 34
	v_readlane_b32 s8, v254, 31
	v_readlane_b32 s9, v254, 32
	v_readlane_b32 s2, v255, 9
	s_nop 3
	v_mov_b32_e32 v0, s0
	ds_read_b32 v1, v0
	s_add_u32 s8, s8, s94
	s_addc_u32 s9, s9, 0
	s_add_u32 s8, s8, 0x1e002000
	s_addc_u32 s9, s9, 0
	s_and_b32 s2, s2, 15
	s_lshl_b32 s2, s2, 7
	s_waitcnt lgkmcnt(0)
	v_add_u32_e32 v1, 1, v1
	ds_write_b32 v0, v1
	s_waitcnt lgkmcnt(0)
	v_readfirstlane_b32 s0, v1
	s_mov_b64 vcc, exec
	s_mov_b64 exec, 1
	v_mov_b32_e32 v0, s2
	v_mov_b32_e32 v1, 1
	global_atomic_add v0, v1, s[8:9]
	s_mov_b64 exec, vcc
	s_add_u32 s2, s58, 15
	v_sub_u32_e32 v0, s2, v232
	v_lshrrev_b32_e32 v0, 4, v0
	v_mul_lo_u32 v0, v0, s0
	s_mov_b32 s2, 0x4000

; DI void flat_barrier(unsigned char* wsb, LAS unsigned char* ldsb) {
;     ...
;         __builtin_amdgcn_fence(__ATOMIC_ACQUIRE, "agent");
;         asm volatile("s_waitcnt vmcnt(0)" ::: "memory");
;     }
;     __syncthreads();
; __global__ void __launch_bounds__(512, 2) mega(Params P) {
;     ...
;         grid.sync();
.Lnb_acqcg:
	buffer_inv sc1
	s_waitcnt vmcnt(0)
	s_branch .LBB0_345
